# EpiUkv SSCKV loads hoisted upfront; P11 residual (h2) loads marked nt
# speedup vs baseline: 1.0254x; 1.0009x over previous
.LBB0_897:
	v_lshl_add_u32 v144, s26, 8, v148
	v_ashrrev_i32_e32 v145, 31, v144
	v_lshl_add_u64 v[146:147], v[144:145], 4, s[24:25]
	v_mov_b64_e32 v[244:245], v[146:147]
	global_load_dwordx4 v[212:215], v[244:245], off
	global_load_dwordx4 v[216:219], v[244:245], off offset:256
	global_load_dwordx4 v[220:223], v[244:245], off offset:512
	global_load_dwordx4 v[224:227], v[244:245], off offset:768
	global_load_dwordx4 v[228:231], v[244:245], off offset:2048
	global_load_dwordx4 v[232:235], v[244:245], off offset:2304
	global_load_dwordx4 v[236:239], v[244:245], off offset:2560
	global_load_dwordx4 v[240:243], v[244:245], off offset:2816
	s_cmp_eq_u32 s52, 0
	v_lshlrev_b64 v[146:147], 9, v[144:145]
	v_lshlrev_b64 v[160:161], 10, v[144:145]
	s_cselect_b64 vcc, -1, 0
	s_lshl_b32 s9, s52, 8
	s_add_i32 s30, s9, 0xffffff00
	s_ashr_i32 s31, s30, 31
	v_lshl_add_u64 v[162:163], v[138:139], 0, v[146:147]
	v_lshl_add_u64 v[146:147], s[30:31], 1, v[136:137]
	v_or_b32_e32 v158, 16, v144
	v_ashrrev_i32_e32 v159, 31, v158
	v_lshl_add_u64 v[164:165], v[158:159], 4, s[24:25]
	s_waitcnt vmcnt(7)
	v_mov_b64_e32 v[154:155], v[212:213]
	v_mov_b64_e32 v[156:157], v[214:215]
	v_mov_b32_e32 v166, v155
	v_mov_b32_e32 v167, v156
	v_mov_b32_e32 v155, v157
	v_pk_add_f32 v[154:155], v[166:167], v[154:155]
	v_lshl_add_u64 v[156:157], v[146:147], 0, v[160:161]
	v_add_f32_e32 v145, v154, v155
	v_fmamk_f32 v145, v145, 0x3b800000, v153
	v_rsq_f32_e32 v154, v145
	v_cndmask_b32_e32 v157, v157, v163, vcc
	v_cndmask_b32_e32 v156, v156, v162, vcc
	v_pk_mul_f32 v[126:127], v[126:127], v[154:155] op_sel_hi:[1,0]
	v_pk_mul_f32 v[124:125], v[124:125], v[154:155] op_sel_hi:[1,0]
	v_pk_mul_f32 v[122:123], v[122:123], v[154:155] op_sel_hi:[1,0]
	v_pk_mul_f32 v[120:121], v[120:121], v[154:155] op_sel_hi:[1,0]
	v_pk_mul_f32 v[118:119], v[118:119], v[154:155] op_sel_hi:[1,0]
	v_pk_mul_f32 v[116:117], v[116:117], v[154:155] op_sel_hi:[1,0]
	v_pk_mul_f32 v[160:161], v[114:115], v[154:155] op_sel_hi:[1,0]
	v_pk_mul_f32 v[154:155], v[112:113], v[154:155] op_sel_hi:[1,0]
	v_cvt_pk_bf16_f32 v112, v124, v125
	v_cvt_pk_bf16_f32 v113, v126, v127
	v_cvt_pk_bf16_f32 v114, v120, v121
	v_cvt_pk_bf16_f32 v115, v122, v123
	global_store_dwordx4 v[156:157], v[112:115], off
	v_lshlrev_b64 v[120:121], 10, v[158:159]
	s_nop 0
	v_cvt_pk_bf16_f32 v112, v116, v117
	v_cvt_pk_bf16_f32 v113, v118, v119
	v_cvt_pk_bf16_f32 v114, v154, v155
	v_cvt_pk_bf16_f32 v115, v160, v161
	global_store_dwordx4 v[156:157], v[112:115], off offset:256
	v_lshlrev_b64 v[118:119], 9, v[158:159]
	v_lshl_add_u64 v[118:119], v[138:139], 0, v[118:119]
	v_or_b32_e32 v116, 32, v144
	v_ashrrev_i32_e32 v117, 31, v116
	v_lshl_add_u64 v[122:123], v[116:117], 4, s[24:25]
	s_waitcnt vmcnt(8)
	v_mov_b64_e32 v[112:113], v[216:217]
	v_mov_b64_e32 v[114:115], v[218:219]
	v_mov_b32_e32 v124, v113
	v_mov_b32_e32 v125, v114
	v_mov_b32_e32 v113, v115
	v_pk_add_f32 v[112:113], v[124:125], v[112:113]
	v_lshl_add_u64 v[114:115], v[146:147], 0, v[120:121]
	v_add_f32_e32 v112, v112, v113
	v_fmamk_f32 v112, v112, 0x3b800000, v153
	v_rsq_f32_e32 v112, v112
	v_cndmask_b32_e32 v115, v115, v119, vcc
	v_cndmask_b32_e32 v114, v114, v118, vcc
	v_pk_mul_f32 v[110:111], v[110:111], v[112:113] op_sel_hi:[1,0]
	v_pk_mul_f32 v[108:109], v[108:109], v[112:113] op_sel_hi:[1,0]
	v_pk_mul_f32 v[106:107], v[106:107], v[112:113] op_sel_hi:[1,0]
	v_pk_mul_f32 v[104:105], v[104:105], v[112:113] op_sel_hi:[1,0]
	v_pk_mul_f32 v[102:103], v[102:103], v[112:113] op_sel_hi:[1,0]
	v_pk_mul_f32 v[100:101], v[100:101], v[112:113] op_sel_hi:[1,0]
	v_pk_mul_f32 v[118:119], v[98:99], v[112:113] op_sel_hi:[1,0]
	v_pk_mul_f32 v[112:113], v[96:97], v[112:113] op_sel_hi:[1,0]
	v_cvt_pk_bf16_f32 v96, v108, v109
	v_cvt_pk_bf16_f32 v97, v110, v111
	v_cvt_pk_bf16_f32 v98, v104, v105
	v_cvt_pk_bf16_f32 v99, v106, v107
	global_store_dwordx4 v[114:115], v[96:99], off
	v_lshlrev_b64 v[104:105], 10, v[116:117]
	s_nop 0
	v_cvt_pk_bf16_f32 v96, v100, v101
	v_cvt_pk_bf16_f32 v97, v102, v103
	v_cvt_pk_bf16_f32 v98, v112, v113
	v_cvt_pk_bf16_f32 v99, v118, v119
	global_store_dwordx4 v[114:115], v[96:99], off offset:256
	v_lshlrev_b64 v[102:103], 9, v[116:117]
	v_lshl_add_u64 v[102:103], v[138:139], 0, v[102:103]
	v_or_b32_e32 v100, 48, v144
	v_ashrrev_i32_e32 v101, 31, v100
	v_lshl_add_u64 v[106:107], v[100:101], 4, s[24:25]
	s_waitcnt vmcnt(9)
	v_mov_b64_e32 v[96:97], v[220:221]
	v_mov_b64_e32 v[98:99], v[222:223]
	v_mov_b32_e32 v108, v97
	v_mov_b32_e32 v109, v98
	v_mov_b32_e32 v97, v99
	v_pk_add_f32 v[96:97], v[108:109], v[96:97]
	v_lshl_add_u64 v[98:99], v[146:147], 0, v[104:105]
	v_add_f32_e32 v96, v96, v97
	v_fmamk_f32 v96, v96, 0x3b800000, v153
	v_rsq_f32_e32 v96, v96
	v_cndmask_b32_e32 v99, v99, v103, vcc
	v_cndmask_b32_e32 v98, v98, v102, vcc
	v_pk_mul_f32 v[94:95], v[94:95], v[96:97] op_sel_hi:[1,0]
	v_pk_mul_f32 v[92:93], v[92:93], v[96:97] op_sel_hi:[1,0]
	v_pk_mul_f32 v[90:91], v[90:91], v[96:97] op_sel_hi:[1,0]
	v_pk_mul_f32 v[88:89], v[88:89], v[96:97] op_sel_hi:[1,0]
	v_pk_mul_f32 v[86:87], v[86:87], v[96:97] op_sel_hi:[1,0]
	v_pk_mul_f32 v[84:85], v[84:85], v[96:97] op_sel_hi:[1,0]
	v_pk_mul_f32 v[102:103], v[82:83], v[96:97] op_sel_hi:[1,0]
	v_pk_mul_f32 v[96:97], v[80:81], v[96:97] op_sel_hi:[1,0]
	v_cvt_pk_bf16_f32 v80, v92, v93
	v_cvt_pk_bf16_f32 v81, v94, v95
	v_cvt_pk_bf16_f32 v82, v88, v89
	v_cvt_pk_bf16_f32 v83, v90, v91
	global_store_dwordx4 v[98:99], v[80:83], off
	v_lshlrev_b64 v[88:89], 10, v[100:101]
	s_nop 0
	v_cvt_pk_bf16_f32 v80, v84, v85
	v_cvt_pk_bf16_f32 v81, v86, v87
	v_cvt_pk_bf16_f32 v82, v96, v97
	v_cvt_pk_bf16_f32 v83, v102, v103
	global_store_dwordx4 v[98:99], v[80:83], off offset:256
	v_lshlrev_b64 v[86:87], 9, v[100:101]
	v_lshl_add_u64 v[86:87], v[138:139], 0, v[86:87]
	v_add_u32_e32 v84, 0x80, v144
	v_ashrrev_i32_e32 v85, 31, v84
	v_lshl_add_u64 v[90:91], v[84:85], 4, s[24:25]
	s_waitcnt vmcnt(10)
	v_mov_b64_e32 v[80:81], v[224:225]
	v_mov_b64_e32 v[82:83], v[226:227]
	v_mov_b32_e32 v92, v81
	v_mov_b32_e32 v93, v82
	v_mov_b32_e32 v81, v83
	v_pk_add_f32 v[80:81], v[92:93], v[80:81]
	v_lshl_add_u64 v[82:83], v[146:147], 0, v[88:89]
	v_add_f32_e32 v80, v80, v81
	v_fmamk_f32 v80, v80, 0x3b800000, v153
	v_rsq_f32_e32 v80, v80
	v_cndmask_b32_e32 v83, v83, v87, vcc
	v_cndmask_b32_e32 v82, v82, v86, vcc
	v_pk_mul_f32 v[78:79], v[78:79], v[80:81] op_sel_hi:[1,0]
	v_pk_mul_f32 v[76:77], v[76:77], v[80:81] op_sel_hi:[1,0]
	v_pk_mul_f32 v[74:75], v[74:75], v[80:81] op_sel_hi:[1,0]
	v_pk_mul_f32 v[72:73], v[72:73], v[80:81] op_sel_hi:[1,0]
	v_pk_mul_f32 v[70:71], v[70:71], v[80:81] op_sel_hi:[1,0]
	v_pk_mul_f32 v[68:69], v[68:69], v[80:81] op_sel_hi:[1,0]
	v_pk_mul_f32 v[86:87], v[66:67], v[80:81] op_sel_hi:[1,0]
	v_pk_mul_f32 v[80:81], v[64:65], v[80:81] op_sel_hi:[1,0]
	v_cvt_pk_bf16_f32 v64, v76, v77
	v_cvt_pk_bf16_f32 v65, v78, v79
	v_cvt_pk_bf16_f32 v66, v72, v73
	v_cvt_pk_bf16_f32 v67, v74, v75
	global_store_dwordx4 v[82:83], v[64:67], off
	v_lshlrev_b64 v[72:73], 10, v[84:85]
	s_nop 0
	v_cvt_pk_bf16_f32 v64, v68, v69
	v_cvt_pk_bf16_f32 v65, v70, v71
	v_cvt_pk_bf16_f32 v66, v80, v81
	v_cvt_pk_bf16_f32 v67, v86, v87
	global_store_dwordx4 v[82:83], v[64:67], off offset:256
	v_lshlrev_b64 v[70:71], 9, v[84:85]
	v_lshl_add_u64 v[70:71], v[138:139], 0, v[70:71]
	v_add_u32_e32 v68, 0x90, v144
	v_ashrrev_i32_e32 v69, 31, v68
	v_lshl_add_u64 v[74:75], v[68:69], 4, s[24:25]
	s_waitcnt vmcnt(11)
	v_mov_b64_e32 v[64:65], v[228:229]
	v_mov_b64_e32 v[66:67], v[230:231]
	v_mov_b32_e32 v76, v65
	v_mov_b32_e32 v77, v66
	v_mov_b32_e32 v65, v67
	v_pk_add_f32 v[64:65], v[76:77], v[64:65]
	v_lshl_add_u64 v[66:67], v[146:147], 0, v[72:73]
	v_add_f32_e32 v64, v64, v65
	v_fmamk_f32 v64, v64, 0x3b800000, v153
	v_rsq_f32_e32 v64, v64
	v_cndmask_b32_e32 v67, v67, v71, vcc
	v_cndmask_b32_e32 v66, v66, v70, vcc
	v_pk_mul_f32 v[62:63], v[62:63], v[64:65] op_sel_hi:[1,0]
	v_pk_mul_f32 v[60:61], v[60:61], v[64:65] op_sel_hi:[1,0]
	v_pk_mul_f32 v[58:59], v[58:59], v[64:65] op_sel_hi:[1,0]
	v_pk_mul_f32 v[56:57], v[56:57], v[64:65] op_sel_hi:[1,0]
	v_pk_mul_f32 v[54:55], v[54:55], v[64:65] op_sel_hi:[1,0]
	v_pk_mul_f32 v[52:53], v[52:53], v[64:65] op_sel_hi:[1,0]
	v_pk_mul_f32 v[70:71], v[50:51], v[64:65] op_sel_hi:[1,0]
	v_pk_mul_f32 v[64:65], v[48:49], v[64:65] op_sel_hi:[1,0]
	v_cvt_pk_bf16_f32 v48, v60, v61
	v_cvt_pk_bf16_f32 v49, v62, v63
	v_cvt_pk_bf16_f32 v50, v56, v57
	v_cvt_pk_bf16_f32 v51, v58, v59
	global_store_dwordx4 v[66:67], v[48:51], off
	v_lshlrev_b64 v[56:57], 10, v[68:69]
	s_nop 0
	v_cvt_pk_bf16_f32 v48, v52, v53
	v_cvt_pk_bf16_f32 v49, v54, v55
	v_cvt_pk_bf16_f32 v50, v64, v65
	v_cvt_pk_bf16_f32 v51, v70, v71
	global_store_dwordx4 v[66:67], v[48:51], off offset:256
	v_lshlrev_b64 v[54:55], 9, v[68:69]
	v_lshl_add_u64 v[54:55], v[138:139], 0, v[54:55]
	v_add_u32_e32 v52, 0xa0, v144
	v_ashrrev_i32_e32 v53, 31, v52
	v_lshl_add_u64 v[58:59], v[52:53], 4, s[24:25]
	s_waitcnt vmcnt(12)
	v_mov_b64_e32 v[48:49], v[232:233]
	v_mov_b64_e32 v[50:51], v[234:235]
	v_mov_b32_e32 v60, v49
	v_mov_b32_e32 v61, v50
	v_mov_b32_e32 v49, v51
	v_pk_add_f32 v[48:49], v[60:61], v[48:49]
	v_lshl_add_u64 v[50:51], v[146:147], 0, v[56:57]
	v_add_f32_e32 v48, v48, v49
	v_fmamk_f32 v48, v48, 0x3b800000, v153
	v_rsq_f32_e32 v48, v48
	v_cndmask_b32_e32 v51, v51, v55, vcc
	v_cndmask_b32_e32 v50, v50, v54, vcc
	v_pk_mul_f32 v[46:47], v[46:47], v[48:49] op_sel_hi:[1,0]
	v_pk_mul_f32 v[44:45], v[44:45], v[48:49] op_sel_hi:[1,0]
	v_pk_mul_f32 v[42:43], v[42:43], v[48:49] op_sel_hi:[1,0]
	v_pk_mul_f32 v[40:41], v[40:41], v[48:49] op_sel_hi:[1,0]
	v_pk_mul_f32 v[38:39], v[38:39], v[48:49] op_sel_hi:[1,0]
	v_pk_mul_f32 v[36:37], v[36:37], v[48:49] op_sel_hi:[1,0]
	v_pk_mul_f32 v[54:55], v[34:35], v[48:49] op_sel_hi:[1,0]
	v_pk_mul_f32 v[48:49], v[32:33], v[48:49] op_sel_hi:[1,0]
	v_cvt_pk_bf16_f32 v32, v44, v45
	v_cvt_pk_bf16_f32 v33, v46, v47
	v_cvt_pk_bf16_f32 v34, v40, v41
	v_cvt_pk_bf16_f32 v35, v42, v43
	global_store_dwordx4 v[50:51], v[32:35], off
	v_lshlrev_b64 v[40:41], 10, v[52:53]
	s_nop 0
	v_cvt_pk_bf16_f32 v32, v36, v37
	v_cvt_pk_bf16_f32 v33, v38, v39
	v_cvt_pk_bf16_f32 v34, v48, v49
	v_cvt_pk_bf16_f32 v35, v54, v55
	global_store_dwordx4 v[50:51], v[32:35], off offset:256
	v_lshlrev_b64 v[38:39], 9, v[52:53]
	v_lshl_add_u64 v[38:39], v[138:139], 0, v[38:39]
	v_add_u32_e32 v36, 0xb0, v144
	v_ashrrev_i32_e32 v37, 31, v36
	v_lshl_add_u64 v[42:43], v[36:37], 4, s[24:25]
	s_waitcnt vmcnt(13)
	v_mov_b64_e32 v[32:33], v[236:237]
	v_mov_b64_e32 v[34:35], v[238:239]
	v_mov_b32_e32 v44, v33
	v_mov_b32_e32 v45, v34
	v_mov_b32_e32 v33, v35
	v_pk_add_f32 v[32:33], v[44:45], v[32:33]
	v_lshl_add_u64 v[34:35], v[146:147], 0, v[40:41]
	v_add_f32_e32 v32, v32, v33
	v_fmamk_f32 v32, v32, 0x3b800000, v153
	v_rsq_f32_e32 v32, v32
	v_cndmask_b32_e32 v35, v35, v39, vcc
	v_cndmask_b32_e32 v34, v34, v38, vcc
	v_pk_mul_f32 v[30:31], v[30:31], v[32:33] op_sel_hi:[1,0]
	v_pk_mul_f32 v[28:29], v[28:29], v[32:33] op_sel_hi:[1,0]
	v_pk_mul_f32 v[26:27], v[26:27], v[32:33] op_sel_hi:[1,0]
	v_pk_mul_f32 v[24:25], v[24:25], v[32:33] op_sel_hi:[1,0]
	v_pk_mul_f32 v[22:23], v[22:23], v[32:33] op_sel_hi:[1,0]
	v_pk_mul_f32 v[20:21], v[20:21], v[32:33] op_sel_hi:[1,0]
	v_pk_mul_f32 v[38:39], v[18:19], v[32:33] op_sel_hi:[1,0]
	v_pk_mul_f32 v[32:33], v[16:17], v[32:33] op_sel_hi:[1,0]
	v_cvt_pk_bf16_f32 v16, v28, v29
	v_cvt_pk_bf16_f32 v17, v30, v31
	v_cvt_pk_bf16_f32 v18, v24, v25
	v_cvt_pk_bf16_f32 v19, v26, v27
	global_store_dwordx4 v[34:35], v[16:19], off
	s_nop 1
	v_cvt_pk_bf16_f32 v16, v20, v21
	v_cvt_pk_bf16_f32 v17, v22, v23
	v_cvt_pk_bf16_f32 v18, v32, v33
	v_cvt_pk_bf16_f32 v19, v38, v39
	global_store_dwordx4 v[34:35], v[16:19], off offset:256
	v_lshlrev_b64 v[20:21], 9, v[36:37]
	v_lshlrev_b64 v[22:23], 10, v[36:37]
	v_lshl_add_u64 v[20:21], v[138:139], 0, v[20:21]
	s_waitcnt vmcnt(14)
	v_mov_b64_e32 v[16:17], v[240:241]
	v_mov_b64_e32 v[18:19], v[242:243]
	v_mov_b32_e32 v24, v17
	v_mov_b32_e32 v25, v18
	v_mov_b32_e32 v17, v19
	v_pk_add_f32 v[16:17], v[24:25], v[16:17]
	v_lshl_add_u64 v[18:19], v[146:147], 0, v[22:23]
	v_add_f32_e32 v16, v16, v17
	v_fmamk_f32 v16, v16, 0x3b800000, v153
	v_rsq_f32_e32 v16, v16
	v_cndmask_b32_e32 v19, v19, v21, vcc
	v_cndmask_b32_e32 v18, v18, v20, vcc
	s_andn2_b64 vcc, exec, s[4:5]
	v_pk_mul_f32 v[14:15], v[14:15], v[16:17] op_sel_hi:[1,0]
	v_pk_mul_f32 v[12:13], v[12:13], v[16:17] op_sel_hi:[1,0]
	v_pk_mul_f32 v[10:11], v[10:11], v[16:17] op_sel_hi:[1,0]
	v_pk_mul_f32 v[8:9], v[8:9], v[16:17] op_sel_hi:[1,0]
	v_pk_mul_f32 v[6:7], v[6:7], v[16:17] op_sel_hi:[1,0]
	v_pk_mul_f32 v[4:5], v[4:5], v[16:17] op_sel_hi:[1,0]
	v_pk_mul_f32 v[20:21], v[2:3], v[16:17] op_sel_hi:[1,0]
	v_pk_mul_f32 v[16:17], v[0:1], v[16:17] op_sel_hi:[1,0]
	v_cvt_pk_bf16_f32 v0, v12, v13
	v_cvt_pk_bf16_f32 v1, v14, v15
	v_cvt_pk_bf16_f32 v2, v8, v9
	v_cvt_pk_bf16_f32 v3, v10, v11
	global_store_dwordx4 v[18:19], v[0:3], off
	s_mov_b64 s[4:5], -1
	s_nop 0
	v_cvt_pk_bf16_f32 v0, v4, v5
	v_cvt_pk_bf16_f32 v1, v6, v7
	v_cvt_pk_bf16_f32 v2, v16, v17
	v_cvt_pk_bf16_f32 v3, v20, v21
	global_store_dwordx4 v[18:19], v[0:3], off offset:256
	s_cbranch_vccnz .LBB0_890
	s_andn2_b64 vcc, exec, s[0:1]
	s_cbranch_vccnz .LBB0_889
	s_barrier
	s_branch .LBB0_889

.LBB0_1328:
	s_lshl_b32 s21, s45, 8
	v_lshl_or_b32 v190, s20, 8, v208
	v_add_u32_e32 v192, s21, v204
	s_ashr_i32 s4, s45, 3
	v_ashrrev_i32_e32 v191, 31, v190
	v_ashrrev_i32_e32 v193, 31, v192
	s_mul_hi_i32 s5, s4, 0x9000
	s_mul_i32 s4, s4, 0x9000
	v_lshl_add_u64 v[202:203], v[190:191], 1, s[74:75]
	v_lshlrev_b64 v[120:121], 11, v[192:193]
	s_add_u32 s4, s60, s4
	v_lshl_add_u64 v[120:121], v[202:203], 0, v[120:121]
	s_addc_u32 s5, s61, s5
	v_mbcnt_lo_u32_b32 v213, -1, 0
	v_mbcnt_hi_u32_b32 v213, -1, v213
	global_load_dwordx4 v[194:197], v[120:121], off nt
	global_load_dwordx4 v[198:201], v[120:121], off offset:256 nt
	v_lshl_add_u64 v[120:121], v[190:191], 2, s[4:5]
	v_add_co_u32_e32 v122, vcc, s39, v120
	v_lshl_add_u64 v[128:129], v[120:121], 0, s[12:13]
	s_nop 0
	v_addc_co_u32_e32 v123, vcc, 0, v121, vcc
	global_load_dwordx4 v[140:143], v[122:123], off
	global_load_dwordx4 v[136:139], v[128:129], off offset:16
	s_nop 0
	global_load_dwordx4 v[128:131], v[122:123], off offset:512
	v_lshl_add_u64 v[120:121], v[120:121], 0, s[14:15]
	global_load_dwordx4 v[120:123], v[120:121], off offset:16
	v_or_b32_e32 v188, 16, v192
	v_or_b32_e32 v186, 32, v192
	v_or_b32_e32 v184, 48, v192
	v_ashrrev_i32_e32 v189, 31, v188
	v_ashrrev_i32_e32 v187, 31, v186
	v_ashrrev_i32_e32 v185, 31, v184
	v_lshlrev_b64 v[144:145], 11, v[188:189]
	v_lshlrev_b64 v[146:147], 11, v[186:187]
	v_lshlrev_b64 v[148:149], 11, v[184:185]
	v_lshl_add_u64 v[144:145], v[202:203], 0, v[144:145]
	v_lshl_add_u64 v[146:147], v[202:203], 0, v[146:147]
	v_lshl_add_u64 v[216:217], v[202:203], 0, v[148:149]
	global_load_dwordx4 v[164:167], v[144:145], off nt
	global_load_dwordx4 v[160:163], v[144:145], off offset:256 nt
	global_load_dwordx4 v[156:159], v[146:147], off nt
	global_load_dwordx4 v[152:155], v[146:147], off offset:256 nt
	global_load_dwordx4 v[148:151], v[216:217], off nt
	s_nop 0
	global_load_dwordx4 v[144:147], v[216:217], off offset:256 nt
	v_and_b32_e32 v216, 64, v214
	v_add_u32_e32 v224, 64, v216
	s_waitcnt vmcnt(0)
	v_xor_b32_e32 v215, 16, v214
	v_cmp_lt_i32_e32 vcc, v215, v224
	v_lshlrev_b32_e32 v216, 16, v194
	v_and_b32_e32 v217, 0xffff0000, v194
	v_lshlrev_b32_e32 v194, 16, v195
	v_and_b32_e32 v195, 0xffff0000, v195
	v_lshlrev_b32_e32 v218, 16, v196
	v_and_b32_e32 v219, 0xffff0000, v196
	v_lshlrev_b32_e32 v196, 16, v197
	v_and_b32_e32 v197, 0xffff0000, v197
	v_lshlrev_b32_e32 v220, 16, v198
	v_and_b32_e32 v221, 0xffff0000, v198
	v_lshlrev_b32_e32 v198, 16, v199
	v_and_b32_e32 v199, 0xffff0000, v199
	v_pk_fma_f32 v[134:135], v[134:135], v[142:143], v[194:195]
	v_pk_fma_f32 v[132:133], v[132:133], v[140:141], v[216:217]
	v_pk_fma_f32 v[126:127], v[126:127], v[138:139], v[196:197]
	v_pk_fma_f32 v[124:125], v[124:125], v[136:137], v[218:219]
	v_pk_fma_f32 v[118:119], v[118:119], v[130:131], v[198:199]
	v_pk_fma_f32 v[116:117], v[116:117], v[128:129], v[220:221]
	v_mul_f32_e32 v194, v133, v133
	v_mul_f32_e32 v195, v135, v135
	v_mul_f32_e32 v196, v125, v125
	v_mul_f32_e32 v197, v127, v127
	v_mul_f32_e32 v198, v117, v117
	v_mul_f32_e32 v199, v119, v119
	v_fmac_f32_e32 v194, v132, v132
	v_fmac_f32_e32 v195, v134, v134
	v_fmac_f32_e32 v196, v124, v124
	v_fmac_f32_e32 v197, v126, v126
	v_lshlrev_b32_e32 v222, 16, v200
	v_and_b32_e32 v223, 0xffff0000, v200
	v_lshlrev_b32_e32 v200, 16, v201
	v_and_b32_e32 v201, 0xffff0000, v201
	v_fmac_f32_e32 v198, v116, v116
	v_fmac_f32_e32 v199, v118, v118
	v_add_f32_e32 v194, v194, v195
	v_add_f32_e32 v195, v196, v197
	v_pk_fma_f32 v[114:115], v[114:115], v[122:123], v[200:201]
	v_pk_fma_f32 v[112:113], v[112:113], v[120:121], v[222:223]
	v_add_f32_e32 v196, v198, v199
	v_add_f32_e32 v194, v194, v195
	v_add_f32_e32 v194, v194, v196
	v_mul_f32_e32 v195, v113, v113
	v_mul_f32_e32 v196, v115, v115
	v_fmac_f32_e32 v195, v112, v112
	v_fmac_f32_e32 v196, v114, v114
	v_cndmask_b32_e32 v215, v214, v215, vcc
	v_add_f32_e32 v195, v195, v196
	v_lshlrev_b32_e32 v215, 2, v215
	v_add_f32_e32 v194, v194, v195
	ds_bpermute_b32 v195, v215, v194
	v_xor_b32_e32 v196, 32, v214
	v_cmp_lt_i32_e32 vcc, v196, v224
	s_waitcnt lgkmcnt(0)
	v_add_f32_e32 v194, v194, v195
	v_cndmask_b32_e32 v196, v214, v196, vcc
	v_lshlrev_b32_e32 v216, 2, v196
	ds_bpermute_b32 v195, v216, v194
	s_and_saveexec_b64 s[4:5], s[0:1]
	s_cbranch_execz .LBB0_1330
	s_waitcnt lgkmcnt(0)
	v_add_f32_e32 v194, v194, v195
	ds_write_b32 v206, v194

.LBB0_1336:
	s_or_b64 exec, exec, s[4:5]
	v_add_u32_e32 v198, 0x80, v192
	v_ashrrev_i32_e32 v199, 31, v198
	s_waitcnt lgkmcnt(0)
	v_lshlrev_b64 v[64:65], 11, v[198:199]
	v_lshl_add_u64 v[64:65], v[202:203], 0, v[64:65]
	global_load_dwordx4 v[218:221], v[64:65], off nt
	global_load_dwordx4 v[222:225], v[64:65], off offset:256 nt
	v_add_u32_e32 v144, 0x90, v192
	v_add_u32_e32 v90, 0xa0, v192
	v_add_u32_e32 v88, 0xb0, v192
	v_ashrrev_i32_e32 v145, 31, v144
	v_ashrrev_i32_e32 v91, 31, v90
	v_ashrrev_i32_e32 v89, 31, v88
	v_lshlrev_b64 v[64:65], 11, v[144:145]
	v_lshlrev_b64 v[66:67], 11, v[90:91]
	v_lshlrev_b64 v[68:69], 11, v[88:89]
	v_lshl_add_u64 v[64:65], v[202:203], 0, v[64:65]
	v_lshl_add_u64 v[66:67], v[202:203], 0, v[66:67]
	v_lshl_add_u64 v[202:203], v[202:203], 0, v[68:69]
	global_load_dwordx4 v[84:87], v[64:65], off nt
	global_load_dwordx4 v[80:83], v[64:65], off offset:256 nt
	global_load_dwordx4 v[76:79], v[66:67], off nt
	global_load_dwordx4 v[72:75], v[66:67], off offset:256 nt
	global_load_dwordx4 v[68:71], v[202:203], off nt
	s_nop 0
	global_load_dwordx4 v[64:67], v[202:203], off offset:256 nt
	s_waitcnt vmcnt(7)
	v_lshlrev_b32_e32 v202, 16, v218
	v_and_b32_e32 v203, 0xffff0000, v218
	v_lshlrev_b32_e32 v218, 16, v219
	v_and_b32_e32 v219, 0xffff0000, v219
	v_lshlrev_b32_e32 v226, 16, v220
	v_and_b32_e32 v227, 0xffff0000, v220
	v_lshlrev_b32_e32 v220, 16, v221
	v_and_b32_e32 v221, 0xffff0000, v221
	s_waitcnt vmcnt(6)
	v_lshlrev_b32_e32 v228, 16, v222
	v_and_b32_e32 v229, 0xffff0000, v222
	v_lshlrev_b32_e32 v222, 16, v223
	v_and_b32_e32 v223, 0xffff0000, v223
	v_pk_fma_f32 v[62:63], v[62:63], v[142:143], v[218:219]
	v_pk_fma_f32 v[60:61], v[60:61], v[140:141], v[202:203]
	v_pk_fma_f32 v[58:59], v[58:59], v[138:139], v[220:221]
	v_pk_fma_f32 v[56:57], v[56:57], v[136:137], v[226:227]
	v_lshlrev_b32_e32 v230, 16, v224
	v_and_b32_e32 v231, 0xffff0000, v224
	v_lshlrev_b32_e32 v224, 16, v225
	v_and_b32_e32 v225, 0xffff0000, v225
	v_pk_fma_f32 v[54:55], v[54:55], v[130:131], v[222:223]
	v_pk_fma_f32 v[52:53], v[52:53], v[128:129], v[228:229]
	v_mul_f32_e32 v202, v61, v61
	v_mul_f32_e32 v203, v63, v63
	v_mul_f32_e32 v217, v57, v57
	v_mul_f32_e32 v218, v59, v59
	v_pk_fma_f32 v[50:51], v[50:51], v[122:123], v[224:225]
	v_pk_fma_f32 v[48:49], v[48:49], v[120:121], v[230:231]
	v_mul_f32_e32 v219, v53, v53
	v_mul_f32_e32 v220, v55, v55
	v_fmac_f32_e32 v202, v60, v60
	v_fmac_f32_e32 v203, v62, v62
	v_fmac_f32_e32 v217, v56, v56
	v_fmac_f32_e32 v218, v58, v58
	v_mul_f32_e32 v221, v49, v49
	v_mul_f32_e32 v222, v51, v51
	v_fmac_f32_e32 v219, v52, v52
	v_fmac_f32_e32 v220, v54, v54
	v_add_f32_e32 v202, v202, v203
	v_add_f32_e32 v203, v217, v218
	v_fmac_f32_e32 v221, v48, v48
	v_fmac_f32_e32 v222, v50, v50
	v_add_f32_e32 v217, v219, v220
	v_add_f32_e32 v202, v202, v203
	v_add_f32_e32 v202, v202, v217
	v_add_f32_e32 v203, v221, v222
	v_add_f32_e32 v202, v202, v203
	ds_bpermute_b32 v203, v215, v202
	s_waitcnt lgkmcnt(0)
	v_add_f32_e32 v202, v202, v203
	ds_bpermute_b32 v203, v216, v202
	s_and_saveexec_b64 s[4:5], s[0:1]
	s_cbranch_execz .LBB0_1338
	s_waitcnt lgkmcnt(0)
	v_add_f32_e32 v202, v202, v203
	ds_write_b32 v206, v202 offset:2048
